# attention A: no running max / subtraction (sink folded into l init), on top of v24
# speedup vs baseline: 1.0048x; 1.0045x over previous
.LBB0_772:
	s_waitcnt vmcnt(0)
	v_mul_f32_e32 v167, 0x3fb8aa3b, v0
	s_and_b64 vcc, exec, s[4:5]
	v_mov_b32_e32 v33, 0
	s_waitcnt lgkmcnt(0)
	s_barrier
	s_cbranch_vccnz .LBB0_792
	v_add_u32_e32 v4, s44, v184
	s_lshr_b32 s4, s31, 5
	v_ashrrev_i32_e32 v5, 31, v4
	s_and_b32 s4, s4, 1
	v_lshlrev_b64 v[4:5], 8, v[4:5]
	s_lshl_b32 s4, s4, 7
	v_lshl_add_u64 v[4:5], s[24:25], 0, v[4:5]
	s_and_b32 s5, s40, 0x780
	v_or_b32_e32 v4, s4, v4
	v_or_b32_e32 v0, s5, v178
	v_lshl_add_u64 v[168:169], v[158:159], 0, v[4:5]
	v_add_u32_e32 v4, s44, v185
	v_sub_u32_e32 v191, v4, v0
	v_add_u32_e32 v4, s44, v180
	v_ashrrev_i32_e32 v5, 31, v4
	v_lshlrev_b64 v[4:5], 8, v[4:5]
	v_lshl_add_u64 v[4:5], s[24:25], 0, v[4:5]
	v_lshl_add_u64 v[2:3], s[24:25], 0, v[2:3]
	v_or_b32_e32 v4, s4, v4
	v_or_b32_e32 v2, s4, v2
	v_lshl_add_u64 v[170:171], v[160:161], 0, v[4:5]
	v_lshl_add_u64 v[172:173], v[162:163], 0, v[2:3]
	v_mov_b32_e32 v2, v1
	v_mov_b32_e32 v3, v1
	v_mov_b32_e32 v4, v1
	v_mov_b32_e32 v5, v1
	v_mov_b32_e32 v6, v1
	v_mov_b32_e32 v7, v1
	v_mov_b32_e32 v8, v1
	v_mov_b32_e32 v9, v1
	v_mov_b32_e32 v10, v1
	v_mov_b32_e32 v11, v1
	v_mov_b32_e32 v12, v1
	v_mov_b32_e32 v13, v1
	v_mov_b32_e32 v14, v1
	v_mov_b32_e32 v15, v1
	v_mov_b32_e32 v16, v1
	v_mov_b32_e32 v17, v1
	v_mov_b32_e32 v18, v1
	v_mov_b32_e32 v19, v1
	v_mov_b32_e32 v20, v1
	v_mov_b32_e32 v21, v1
	v_mov_b32_e32 v22, v1
	v_mov_b32_e32 v23, v1
	v_mov_b32_e32 v24, v1
	v_mov_b32_e32 v25, v1
	v_mov_b32_e32 v26, v1
	v_mov_b32_e32 v27, v1
	v_mov_b32_e32 v28, v1
	v_mov_b32_e32 v29, v1
	v_mov_b32_e32 v30, v1
	v_mov_b32_e32 v31, v1
	v_mov_b32_e32 v0, v1
	v_mov_b64_e32 v[32:33], v[30:31]
	s_add_i32 s26, s42, 3
	v_mov_b64_e32 v[30:31], v[28:29]
	v_mov_b64_e32 v[28:29], v[26:27]
	v_mov_b64_e32 v[26:27], v[24:25]
	v_mov_b64_e32 v[24:25], v[22:23]
	v_mov_b64_e32 v[22:23], v[20:21]
	v_mov_b64_e32 v[20:21], v[18:19]
	v_mov_b64_e32 v[18:19], v[16:17]
	v_mov_b64_e32 v[16:17], v[14:15]
	v_mov_b64_e32 v[14:15], v[12:13]
	v_mov_b64_e32 v[12:13], v[10:11]
	v_mov_b64_e32 v[10:11], v[8:9]
	v_mov_b64_e32 v[8:9], v[6:7]
	v_mov_b64_e32 v[6:7], v[4:5]
	v_mov_b64_e32 v[4:5], v[2:3]
	v_mov_b64_e32 v[2:3], v[0:1]
	v_exp_f32_e32 v0, v167
	s_nop 0
	v_mul_f32_e32 v0, v177, v0
	s_branch .LBB0_775

.LBB0_777:
	v_lshl_add_u64 v[86:87], v[170:171], 0, s[14:15]
	ds_read_b128 v[66:69], v189 offset:9216
	ds_read_b128 v[82:85], v189 offset:13824
	ds_read_b128 v[100:103], v189 offset:9248
	ds_read_b128 v[104:107], v189 offset:13856
	ds_read_b128 v[108:111], v189 offset:9280
	ds_read_b128 v[112:115], v189 offset:9312
	global_load_dwordx4 v[150:153], v[86:87], off
	s_waitcnt lgkmcnt(5)
	v_mfma_f32_32x32x16_bf16 v[66:81], v[66:69], v[130:133], 0
	v_cmp_lt_u32_e32 vcc, s29, v191
	ds_read_b128 v[116:119], v189 offset:13888
	ds_read_b128 v[120:123], v189 offset:13920
	v_cndmask_b32_e32 v98, v176, v34, vcc
	v_add_u32_e32 v34, 32, v191
	v_cmp_lt_u32_e32 vcc, s29, v34
	v_add_u32_e32 v34, 1, v191
	s_nop 0
	v_cndmask_b32_e32 v50, v176, v50, vcc
	v_cmp_lt_u32_e32 vcc, s29, v34
	v_add_u32_e32 v34, 33, v191
	s_waitcnt lgkmcnt(6)
	v_mfma_f32_32x32x16_bf16 v[82:97], v[82:85], v[130:133], 0
	v_cndmask_b32_e32 v99, v176, v35, vcc
	v_cmp_lt_u32_e32 vcc, s29, v34
	v_add_u32_e32 v34, 2, v191
	v_add_u32_e32 v35, 26, v191
	v_cndmask_b32_e32 v51, v176, v51, vcc
	v_cmp_lt_u32_e32 vcc, s29, v34
	v_add_u32_e32 v34, 34, v191
	s_waitcnt lgkmcnt(5)
	v_mfma_f32_32x32x16_bf16 v[66:81], v[100:103], v[134:137], v[66:81]
	v_cndmask_b32_e32 v100, v176, v36, vcc
	v_cmp_lt_u32_e32 vcc, s29, v34
	v_add_u32_e32 v34, 3, v191
	v_add_u32_e32 v36, 27, v191
	v_cndmask_b32_e32 v52, v176, v52, vcc
	v_cmp_lt_u32_e32 vcc, s29, v34
	v_add_u32_e32 v34, 35, v191
	s_waitcnt lgkmcnt(4)
	v_mfma_f32_32x32x16_bf16 v[82:97], v[104:107], v[134:137], v[82:97]
	v_cndmask_b32_e32 v101, v176, v37, vcc
	v_cmp_lt_u32_e32 vcc, s29, v34
	v_add_u32_e32 v34, 8, v191
	s_nop 0
	v_cndmask_b32_e32 v53, v176, v53, vcc
	v_cmp_lt_u32_e32 vcc, s29, v34
	v_add_u32_e32 v34, 40, v191
	s_waitcnt lgkmcnt(3)
	v_mfma_f32_32x32x16_bf16 v[66:81], v[108:111], v[138:141], v[66:81]
	v_cndmask_b32_e32 v102, v176, v38, vcc
	v_cmp_lt_u32_e32 vcc, s29, v34
	v_add_u32_e32 v34, 9, v191
	s_nop 0
	v_cndmask_b32_e32 v54, v176, v54, vcc
	v_cmp_lt_u32_e32 vcc, s29, v34
	v_add_u32_e32 v34, 41, v191
	s_waitcnt lgkmcnt(1)
	v_mfma_f32_32x32x16_bf16 v[82:97], v[116:119], v[138:141], v[82:97]
	v_cndmask_b32_e32 v103, v176, v39, vcc
	v_cmp_lt_u32_e32 vcc, s29, v34
	v_add_u32_e32 v34, 10, v191
	s_nop 0
	v_cndmask_b32_e32 v55, v176, v55, vcc
	v_cmp_lt_u32_e32 vcc, s29, v34
	v_add_u32_e32 v34, 42, v191
	v_mfma_f32_32x32x16_bf16 v[66:81], v[112:115], v[142:145], v[66:81]
	v_cndmask_b32_e32 v104, v176, v40, vcc
	v_cmp_lt_u32_e32 vcc, s29, v34
	v_add_u32_e32 v34, 11, v191
	s_nop 0
	v_cndmask_b32_e32 v56, v176, v56, vcc
	v_cmp_lt_u32_e32 vcc, s29, v34
	v_add_u32_e32 v34, 43, v191
	s_waitcnt lgkmcnt(0)
	v_mfma_f32_32x32x16_bf16 v[82:97], v[120:123], v[142:145], v[82:97]
	v_cndmask_b32_e32 v105, v176, v41, vcc
	v_cmp_lt_u32_e32 vcc, s29, v34
	v_add_u32_e32 v34, 16, v191
	s_nop 0
	v_cndmask_b32_e32 v57, v176, v57, vcc
	v_cmp_lt_u32_e32 vcc, s29, v34
	v_add_u32_e32 v34, 48, v191
	s_nop 0
	v_cndmask_b32_e32 v106, v176, v42, vcc
	v_cmp_lt_u32_e32 vcc, s29, v34
	v_add_u32_e32 v34, 17, v191
	s_nop 0
	v_cndmask_b32_e32 v58, v176, v58, vcc
	v_cmp_lt_u32_e32 vcc, s29, v34
	v_add_u32_e32 v34, 49, v191
	s_nop 0
	v_cndmask_b32_e32 v107, v176, v43, vcc
	v_cmp_lt_u32_e32 vcc, s29, v34
	v_add_u32_e32 v34, 18, v191
	s_nop 0
	v_cndmask_b32_e32 v59, v176, v59, vcc
	v_cmp_lt_u32_e32 vcc, s29, v34
	v_add_u32_e32 v34, 50, v191
	s_nop 0
	v_cndmask_b32_e32 v44, v176, v44, vcc
	v_cmp_lt_u32_e32 vcc, s29, v34
	v_add_u32_e32 v34, 19, v191
	s_nop 0
	v_cndmask_b32_e32 v37, v176, v60, vcc
	v_cmp_lt_u32_e32 vcc, s29, v34
	v_add_u32_e32 v34, 51, v191
	s_nop 0
	v_cndmask_b32_e32 v45, v176, v45, vcc
	v_cmp_lt_u32_e32 vcc, s29, v34
	v_add_u32_e32 v34, 24, v191
	s_nop 0
	v_cndmask_b32_e32 v38, v176, v61, vcc
	v_cmp_lt_u32_e32 vcc, s29, v34
	v_add_u32_e32 v34, 56, v191
	s_nop 0
	v_cndmask_b32_e32 v43, v176, v46, vcc
	v_cmp_lt_u32_e32 vcc, s29, v34
	v_add_u32_e32 v34, 25, v191
	s_nop 0
	v_cndmask_b32_e32 v39, v176, v62, vcc
	v_cmp_lt_u32_e32 vcc, s29, v34
	v_add_u32_e32 v34, 57, v191
	s_nop 0
	v_cndmask_b32_e32 v40, v176, v47, vcc
	v_cmp_lt_u32_e32 vcc, s29, v34
	s_nop 1
	v_cndmask_b32_e32 v34, v176, v63, vcc
	v_cmp_lt_u32_e32 vcc, s29, v35
	v_add_u32_e32 v35, 58, v191
	s_nop 0
	v_cndmask_b32_e32 v41, v176, v48, vcc
	v_cmp_lt_u32_e32 vcc, s29, v35
	s_nop 1
	v_cndmask_b32_e32 v35, v176, v64, vcc
	v_cmp_lt_u32_e32 vcc, s29, v36
	v_add_u32_e32 v36, 59, v191
	s_nop 0
	v_cndmask_b32_e32 v42, v176, v49, vcc
	v_cmp_lt_u32_e32 vcc, s29, v36
	s_nop 1
	v_cndmask_b32_e32 v36, v176, v65, vcc
.LBB0_779:
	v_exp_f32_e32 v98, v98
	v_exp_f32_e32 v99, v99
	v_exp_f32_e32 v114, v50
	v_exp_f32_e32 v115, v51
	v_exp_f32_e32 v100, v100
	v_exp_f32_e32 v101, v101
	v_exp_f32_e32 v116, v52
	v_exp_f32_e32 v117, v53
	v_exp_f32_e32 v102, v102
	v_exp_f32_e32 v103, v103
	v_exp_f32_e32 v118, v54
	v_exp_f32_e32 v119, v55
	v_exp_f32_e32 v104, v104
	v_exp_f32_e32 v105, v105
	v_exp_f32_e32 v120, v56
	v_exp_f32_e32 v121, v57
	v_exp_f32_e32 v106, v106
	v_exp_f32_e32 v107, v107
	v_exp_f32_e32 v122, v58
	v_exp_f32_e32 v108, v44
	v_exp_f32_e32 v123, v59
	v_exp_f32_e32 v109, v45
	ds_read_b64_tr_b16 v[44:45], v183 offset:18432
	ds_read_b64_tr_b16 v[46:47], v183 offset:19968
	ds_read_b64_tr_b16 v[54:55], v183 offset:20032
	ds_read_b64_tr_b16 v[52:53], v183 offset:18496
	v_cvt_pk_bf16_f32 v48, v98, v99
	v_cvt_pk_bf16_f32 v49, v100, v101
	v_cvt_pk_bf16_f32 v50, v102, v103
	v_cvt_pk_bf16_f32 v51, v104, v105
	s_waitcnt lgkmcnt(2)
	s_nop 0
	v_mfma_f32_32x32x16_bf16 v[2:17], v[44:47], v[48:51], v[2:17]
	v_exp_f32_e32 v111, v40
	v_mov_b32_e32 v44, v42
	v_exp_f32_e32 v110, v43
	v_exp_f32_e32 v112, v41
	ds_read_b64_tr_b16 v[40:41], v183 offset:21504
	ds_read_b64_tr_b16 v[42:43], v183 offset:23040
	v_exp_f32_e32 v113, v44
	s_waitcnt lgkmcnt(2)
	v_mfma_f32_32x32x16_bf16 v[18:33], v[52:55], v[48:51], v[18:33]
	ds_read_b64_tr_b16 v[50:51], v183 offset:23104
	ds_read_b64_tr_b16 v[48:49], v183 offset:21568
	v_cvt_pk_bf16_f32 v44, v106, v107
	v_cvt_pk_bf16_f32 v45, v108, v109
	v_cvt_pk_bf16_f32 v46, v110, v111
	v_cvt_pk_bf16_f32 v47, v112, v113
	v_exp_f32_e32 v124, v37
	s_waitcnt lgkmcnt(2)
	v_mfma_f32_32x32x16_bf16 v[2:17], v[40:43], v[44:47], v[2:17]
	v_exp_f32_e32 v125, v38
	v_mov_b32_e32 v37, v39
	ds_read_b64_tr_b16 v[38:39], v183 offset:24576
	ds_read_b64_tr_b16 v[40:41], v183 offset:26112
	v_cvt_pk_bf16_f32 v42, v114, v115
	v_cvt_pk_bf16_f32 v43, v116, v117
	s_waitcnt lgkmcnt(2)
	v_mfma_f32_32x32x16_bf16 v[18:33], v[48:51], v[44:47], v[18:33]
	ds_read_b64_tr_b16 v[48:49], v183 offset:26176
	ds_read_b64_tr_b16 v[46:47], v183 offset:24640
	v_cvt_pk_bf16_f32 v44, v118, v119
	v_cvt_pk_bf16_f32 v45, v120, v121
	v_exp_f32_e32 v127, v34
	v_exp_f32_e32 v126, v37
	v_exp_f32_e32 v128, v35
	s_waitcnt lgkmcnt(2)
	v_mfma_f32_32x32x16_bf16 v[2:17], v[38:41], v[42:45], v[2:17]
	v_mov_b32_e32 v38, v36
	ds_read_b64_tr_b16 v[34:35], v183 offset:27648
	ds_read_b64_tr_b16 v[36:37], v183 offset:29184
	v_exp_f32_e32 v129, v38
	v_cvt_pk_bf16_f32 v38, v122, v123
	v_cvt_pk_bf16_f32 v39, v124, v125
	v_cvt_pk_bf16_f32 v40, v126, v127
	v_cvt_pk_bf16_f32 v41, v128, v129
	s_waitcnt lgkmcnt(2)
	v_mfma_f32_32x32x16_bf16 v[18:33], v[46:49], v[42:45], v[18:33]
	ds_read_b64_tr_b16 v[44:45], v183 offset:29248
	ds_read_b64_tr_b16 v[42:43], v183 offset:27712
	s_andn2_b64 vcc, exec, s[4:5]
	s_waitcnt lgkmcnt(2)
	v_mfma_f32_32x32x16_bf16 v[2:17], v[34:37], v[38:41], v[2:17]
	s_waitcnt lgkmcnt(0)
	v_mfma_f32_32x32x16_bf16 v[18:33], v[42:45], v[38:41], v[18:33]
	s_cbranch_vccnz .LBB0_781
	s_waitcnt vmcnt(1)
	ds_write_b128 v186, v[146:149]

.LBB0_786:
	v_add_f32_e32 v98, 0, v98
	v_add_f32_e32 v99, 0, v99
	v_add_f32_e32 v114, 0, v114
	v_add_f32_e32 v115, 0, v115
	v_add_f32_e32 v98, v100, v98
	v_add_f32_e32 v99, v101, v99
	v_add_f32_e32 v100, v116, v114
	v_add_f32_e32 v101, v117, v115
	v_add_f32_e32 v98, v102, v98
	v_add_f32_e32 v99, v103, v99
	v_add_f32_e32 v100, v118, v100
	v_add_f32_e32 v101, v119, v101
	v_add_f32_e32 v98, v104, v98
	v_add_f32_e32 v99, v105, v99
	v_add_f32_e32 v100, v120, v100
	v_add_f32_e32 v101, v121, v101
	v_add_f32_e32 v98, v106, v98
	v_add_f32_e32 v99, v107, v99
	v_add_f32_e32 v100, v122, v100
	v_add_f32_e32 v101, v123, v101
	v_add_f32_e32 v98, v108, v98
	v_add_f32_e32 v99, v109, v99
	v_add_f32_e32 v100, v124, v100
	v_add_f32_e32 v101, v125, v101
	v_add_f32_e32 v98, v110, v98
	v_add_f32_e32 v99, v111, v99
	v_add_f32_e32 v100, v126, v100
	v_add_f32_e32 v101, v127, v101
	v_add_f32_e32 v98, v112, v98
	v_add_f32_e32 v99, v113, v99
	v_add_f32_e32 v100, v128, v100
	v_add_f32_e32 v101, v129, v101
	v_add_f32_e32 v98, v98, v99
	v_add_f32_e32 v99, v100, v101
	v_add_f32_e32 v98, v98, v99
	v_add_f32_e32 v0, v0, v98
	v_add_u32_e32 v98, 64, v191
	v_cmp_lt_u32_e32 vcc, s29, v98
	s_nop 1
	v_cndmask_b32_e32 v98, v176, v66, vcc
	v_add_u32_e32 v66, 0x60, v191
	v_cmp_lt_u32_e32 vcc, s29, v66
	v_add_u32_e32 v66, 0x41, v191
	s_nop 0
	v_cndmask_b32_e32 v82, v176, v82, vcc
	v_cmp_lt_u32_e32 vcc, s29, v66
	v_add_u32_e32 v66, 0x61, v191
	s_nop 0
	v_cndmask_b32_e32 v99, v176, v67, vcc
	v_cmp_lt_u32_e32 vcc, s29, v66
	v_add_u32_e32 v66, 0x42, v191
	v_add_u32_e32 v67, 0x5a, v191
	v_cndmask_b32_e32 v83, v176, v83, vcc
	v_cmp_lt_u32_e32 vcc, s29, v66
	v_add_u32_e32 v66, 0x62, v191
	s_nop 0
	v_cndmask_b32_e32 v100, v176, v68, vcc
	v_cmp_lt_u32_e32 vcc, s29, v66
	v_add_u32_e32 v66, 0x43, v191
	v_add_u32_e32 v68, 0x5b, v191
	v_cndmask_b32_e32 v84, v176, v84, vcc
	v_cmp_lt_u32_e32 vcc, s29, v66
	v_add_u32_e32 v66, 0x63, v191
	s_nop 0
	v_cndmask_b32_e32 v101, v176, v69, vcc
	v_cmp_lt_u32_e32 vcc, s29, v66
	v_add_u32_e32 v66, 0x48, v191
	s_nop 0
	v_cndmask_b32_e32 v85, v176, v85, vcc
	v_cmp_lt_u32_e32 vcc, s29, v66
	v_add_u32_e32 v66, 0x68, v191
	s_nop 0
	v_cndmask_b32_e32 v102, v176, v70, vcc
	v_cmp_lt_u32_e32 vcc, s29, v66
	v_add_u32_e32 v66, 0x49, v191
	s_nop 0
	v_cndmask_b32_e32 v86, v176, v86, vcc
	v_cmp_lt_u32_e32 vcc, s29, v66
	v_add_u32_e32 v66, 0x69, v191
	s_nop 0
	v_cndmask_b32_e32 v103, v176, v71, vcc
	v_cmp_lt_u32_e32 vcc, s29, v66
	v_add_u32_e32 v66, 0x4a, v191
	s_nop 0
	v_cndmask_b32_e32 v87, v176, v87, vcc
	v_cmp_lt_u32_e32 vcc, s29, v66
	v_add_u32_e32 v66, 0x6a, v191
	s_nop 0
	v_cndmask_b32_e32 v104, v176, v72, vcc
	v_cmp_lt_u32_e32 vcc, s29, v66
	v_add_u32_e32 v66, 0x4b, v191
	s_nop 0
	v_cndmask_b32_e32 v88, v176, v88, vcc
	v_cmp_lt_u32_e32 vcc, s29, v66
	v_add_u32_e32 v66, 0x6b, v191
	s_nop 0
	v_cndmask_b32_e32 v105, v176, v73, vcc
	v_cmp_lt_u32_e32 vcc, s29, v66
	v_add_u32_e32 v66, 0x50, v191
	s_nop 0
	v_cndmask_b32_e32 v89, v176, v89, vcc
	v_cmp_lt_u32_e32 vcc, s29, v66
	v_add_u32_e32 v66, 0x70, v191
	s_nop 0
	v_cndmask_b32_e32 v106, v176, v74, vcc
	v_cmp_lt_u32_e32 vcc, s29, v66
	v_add_u32_e32 v66, 0x51, v191
	s_nop 0
	v_cndmask_b32_e32 v90, v176, v90, vcc
	v_cmp_lt_u32_e32 vcc, s29, v66
	v_add_u32_e32 v66, 0x71, v191
	s_nop 0
	v_cndmask_b32_e32 v107, v176, v75, vcc
	v_cmp_lt_u32_e32 vcc, s29, v66
	v_add_u32_e32 v66, 0x52, v191
	s_nop 0
	v_cndmask_b32_e32 v91, v176, v91, vcc
	v_cmp_lt_u32_e32 vcc, s29, v66
	v_add_u32_e32 v66, 0x72, v191
	s_nop 0
	v_cndmask_b32_e32 v76, v176, v76, vcc
	v_cmp_lt_u32_e32 vcc, s29, v66
	v_add_u32_e32 v66, 0x53, v191
	s_nop 0
	v_cndmask_b32_e32 v69, v176, v92, vcc
	v_cmp_lt_u32_e32 vcc, s29, v66
	v_add_u32_e32 v66, 0x73, v191
	s_nop 0
	v_cndmask_b32_e32 v77, v176, v77, vcc
	v_cmp_lt_u32_e32 vcc, s29, v66
	v_add_u32_e32 v66, 0x58, v191
	s_nop 0
	v_cndmask_b32_e32 v70, v176, v93, vcc
	v_cmp_lt_u32_e32 vcc, s29, v66
	v_add_u32_e32 v66, 0x78, v191
	s_nop 0
	v_cndmask_b32_e32 v75, v176, v78, vcc
	v_cmp_lt_u32_e32 vcc, s29, v66
	v_add_u32_e32 v66, 0x59, v191
	s_nop 0
	v_cndmask_b32_e32 v71, v176, v94, vcc
	v_cmp_lt_u32_e32 vcc, s29, v66
	v_add_u32_e32 v66, 0x79, v191
	s_nop 0
	v_cndmask_b32_e32 v72, v176, v79, vcc
	v_cmp_lt_u32_e32 vcc, s29, v66
	s_nop 1
	v_cndmask_b32_e32 v66, v176, v95, vcc
	v_cmp_lt_u32_e32 vcc, s29, v67
	v_add_u32_e32 v67, 0x7a, v191
	s_nop 0
	v_cndmask_b32_e32 v73, v176, v80, vcc
	v_cmp_lt_u32_e32 vcc, s29, v67
	s_nop 1
	v_cndmask_b32_e32 v67, v176, v96, vcc
	v_cmp_lt_u32_e32 vcc, s29, v68
	v_add_u32_e32 v68, 0x7b, v191
	s_nop 0
	v_cndmask_b32_e32 v74, v176, v81, vcc
	v_cmp_lt_u32_e32 vcc, s29, v68
	s_nop 1
	v_cndmask_b32_e32 v68, v176, v97, vcc
.LBB0_788:
	v_mov_b32_e32 v80, v82
	v_mov_b32_e32 v81, v83
	v_exp_f32_e32 v78, v98
	v_exp_f32_e32 v79, v99
	v_exp_f32_e32 v82, v100
	v_exp_f32_e32 v83, v101
	v_exp_f32_e32 v92, v102
	v_exp_f32_e32 v93, v103
	v_exp_f32_e32 v94, v104
	v_exp_f32_e32 v95, v105
	v_mov_b32_e32 v96, v106
	v_mov_b32_e32 v97, v107
	ds_read_b64_tr_b16 v[98:99], v183 offset:30720
	ds_read_b64_tr_b16 v[100:101], v183 offset:32256
	ds_read_b64_tr_b16 v[108:109], v183 offset:32320
	ds_read_b64_tr_b16 v[106:107], v183 offset:30784
	v_cvt_pk_bf16_f32 v102, v78, v79
	v_cvt_pk_bf16_f32 v103, v82, v83
	v_cvt_pk_bf16_f32 v104, v92, v93
	v_cvt_pk_bf16_f32 v105, v94, v95
	s_waitcnt lgkmcnt(2)
	s_nop 0
	v_mfma_f32_32x32x16_bf16 v[2:17], v[98:101], v[102:105], v[2:17]
	v_exp_f32_e32 v98, v72
	v_exp_f32_e32 v96, v96
	v_exp_f32_e32 v97, v97
	s_waitcnt lgkmcnt(0)
	v_mfma_f32_32x32x16_bf16 v[18:33], v[106:109], v[102:105], v[18:33]
	v_exp_f32_e32 v76, v76
	v_exp_f32_e32 v77, v77
	v_exp_f32_e32 v75, v75
	v_exp_f32_e32 v72, v73
	ds_read_b64_tr_b16 v[110:111], v183 offset:33792
	ds_read_b64_tr_b16 v[112:113], v183 offset:35328
	v_exp_f32_e32 v73, v74
	ds_read_b64_tr_b16 v[106:107], v183 offset:35392
	ds_read_b64_tr_b16 v[104:105], v183 offset:33856
	v_cvt_pk_bf16_f32 v100, v96, v97
	v_cvt_pk_bf16_f32 v101, v76, v77
	v_cvt_pk_bf16_f32 v102, v75, v98
	v_cvt_pk_bf16_f32 v103, v72, v73
	s_waitcnt lgkmcnt(2)
	s_nop 0
	v_mfma_f32_32x32x16_bf16 v[2:17], v[110:113], v[100:103], v[2:17]
	v_exp_f32_e32 v80, v80
	v_exp_f32_e32 v81, v81
	v_exp_f32_e32 v84, v84
	s_waitcnt lgkmcnt(0)
	v_mfma_f32_32x32x16_bf16 v[18:33], v[104:107], v[100:103], v[18:33]
	v_exp_f32_e32 v85, v85
	v_exp_f32_e32 v86, v86
	v_exp_f32_e32 v87, v87
	v_exp_f32_e32 v88, v88
	v_exp_f32_e32 v89, v89
	ds_read_b64_tr_b16 v[108:109], v183 offset:36864
	ds_read_b64_tr_b16 v[110:111], v183 offset:38400
	ds_read_b64_tr_b16 v[106:107], v183 offset:38464
	ds_read_b64_tr_b16 v[104:105], v183 offset:36928
	v_cvt_pk_bf16_f32 v100, v80, v81
	v_cvt_pk_bf16_f32 v101, v84, v85
	v_cvt_pk_bf16_f32 v102, v86, v87
	v_cvt_pk_bf16_f32 v103, v88, v89
	s_waitcnt lgkmcnt(2)
	s_nop 0
	v_mfma_f32_32x32x16_bf16 v[2:17], v[108:111], v[100:103], v[2:17]
	v_exp_f32_e32 v74, v66
	s_waitcnt lgkmcnt(0)
	v_mfma_f32_32x32x16_bf16 v[18:33], v[104:107], v[100:103], v[18:33]
	v_exp_f32_e32 v90, v90
	v_exp_f32_e32 v91, v91
	v_exp_f32_e32 v69, v69
	v_exp_f32_e32 v70, v70
	v_exp_f32_e32 v71, v71
	v_exp_f32_e32 v66, v67
	ds_read_b64_tr_b16 v[108:109], v183 offset:39936
	ds_read_b64_tr_b16 v[110:111], v183 offset:41472
	v_exp_f32_e32 v67, v68
	ds_read_b64_tr_b16 v[106:107], v183 offset:41536
	ds_read_b64_tr_b16 v[104:105], v183 offset:40000
	v_cvt_pk_bf16_f32 v100, v90, v91
	v_cvt_pk_bf16_f32 v101, v69, v70
	v_cvt_pk_bf16_f32 v102, v71, v74
	v_cvt_pk_bf16_f32 v103, v66, v67
	s_andn2_b64 vcc, exec, s[4:5]
	s_waitcnt lgkmcnt(2)
	v_mfma_f32_32x32x16_bf16 v[2:17], v[108:111], v[100:103], v[2:17]
	s_waitcnt lgkmcnt(0)
	v_mfma_f32_32x32x16_bf16 v[18:33], v[104:107], v[100:103], v[18:33]
	s_cbranch_vccnz .LBB0_790
	s_waitcnt vmcnt(0)
	ds_write_b128 v186, v[146:149] offset:9216

.LBB0_792:
	v_mov_b32_e32 v32, v33
	v_mov_b32_e32 v31, v33
	v_mov_b32_e32 v30, v33
	v_mov_b32_e32 v29, v33
	v_mov_b32_e32 v28, v33
	v_mov_b32_e32 v27, v33
	v_mov_b32_e32 v26, v33
	v_mov_b32_e32 v25, v33
	v_mov_b32_e32 v24, v33
	v_mov_b32_e32 v23, v33
	v_mov_b32_e32 v22, v33
	v_mov_b32_e32 v21, v33
	v_mov_b32_e32 v20, v33
	v_mov_b32_e32 v19, v33
	v_mov_b32_e32 v18, v33
	v_mov_b32_e32 v17, v33
	v_mov_b32_e32 v16, v33
	v_mov_b32_e32 v15, v33
	v_mov_b32_e32 v14, v33
	v_mov_b32_e32 v13, v33
	v_mov_b32_e32 v12, v33
	v_mov_b32_e32 v11, v33
	v_mov_b32_e32 v10, v33
	v_mov_b32_e32 v9, v33
	v_mov_b32_e32 v8, v33
	v_mov_b32_e32 v7, v33
	v_mov_b32_e32 v6, v33
	v_mov_b32_e32 v5, v33
	v_mov_b32_e32 v4, v33
	v_mov_b32_e32 v3, v33
	v_mov_b32_e32 v2, v33
	v_exp_f32_e32 v0, v167
	s_nop 0
	v_mul_f32_e32 v0, v177, v0
.LBB0_793:
	s_cmp_gt_i32 s42, s43
	s_cbranch_scc1 .LBB0_797
	v_sub_u32_e32 v66, v181, v190
	v_lshl_add_u32 v71, s42, 6, v66
	v_add_u32_e32 v66, 0xffffff7f, v71
	v_cmp_lt_u32_e32 vcc, s29, v66
	s_nop 1
	v_cndmask_b32_e32 v66, v176, v34, vcc
	v_add_u32_e32 v34, 0xffffff9f, v71
	v_cmp_lt_u32_e32 vcc, s29, v34
	v_add_u32_e32 v34, 0xffffff80, v71
	s_nop 0
	v_cndmask_b32_e32 v50, v176, v50, vcc
	v_cmp_lt_u32_e32 vcc, s29, v34
	v_add_u32_e32 v34, 0xffffffa0, v71
	s_nop 0
	v_cndmask_b32_e32 v67, v176, v35, vcc
	v_cmp_lt_u32_e32 vcc, s29, v34
	v_add_u32_e32 v34, 0xffffff81, v71
	v_add_u32_e32 v35, 0xffffff9a, v71
	v_cndmask_b32_e32 v51, v176, v51, vcc
	v_cmp_lt_u32_e32 vcc, s29, v34
	v_add_u32_e32 v34, 0xffffffa1, v71
	s_nop 0
	v_cndmask_b32_e32 v68, v176, v36, vcc
	v_cmp_lt_u32_e32 vcc, s29, v34
	v_add_u32_e32 v34, 0xffffff82, v71
	s_nop 0
	v_cndmask_b32_e32 v52, v176, v52, vcc
	v_cmp_lt_u32_e32 vcc, s29, v34
	v_add_u32_e32 v34, 0xffffffa2, v71
	s_nop 0
	v_cndmask_b32_e32 v69, v176, v37, vcc
	v_cmp_lt_u32_e32 vcc, s29, v34
	v_add_u32_e32 v34, 0xffffff87, v71
	s_nop 0
	v_cndmask_b32_e32 v53, v176, v53, vcc
	v_cmp_lt_u32_e32 vcc, s29, v34
	v_add_u32_e32 v34, 0xffffffa7, v71
	s_nop 0
	v_cndmask_b32_e32 v70, v176, v38, vcc
	v_cmp_lt_u32_e32 vcc, s29, v34
	v_add_u32_e32 v34, 0xffffff88, v71
	s_nop 0
	v_cndmask_b32_e32 v38, v176, v54, vcc
	v_cmp_lt_u32_e32 vcc, s29, v34
	v_add_u32_e32 v34, 0xffffffa8, v71
	s_nop 0
	v_cndmask_b32_e32 v54, v176, v39, vcc
	v_cmp_lt_u32_e32 vcc, s29, v34
	v_add_u32_e32 v34, 0xffffff89, v71
	s_nop 0
	v_cndmask_b32_e32 v39, v176, v55, vcc
	v_cmp_lt_u32_e32 vcc, s29, v34
	v_add_u32_e32 v34, 0xffffffa9, v71
	s_nop 0
	v_cndmask_b32_e32 v55, v176, v40, vcc
	v_cmp_lt_u32_e32 vcc, s29, v34
	v_add_u32_e32 v34, 0xffffff8a, v71
	s_nop 0
	v_cndmask_b32_e32 v40, v176, v56, vcc
	v_cmp_lt_u32_e32 vcc, s29, v34
	v_add_u32_e32 v34, 0xffffffaa, v71
	s_nop 0
	v_cndmask_b32_e32 v56, v176, v41, vcc
	v_cmp_lt_u32_e32 vcc, s29, v34
	v_add_u32_e32 v34, 0xffffff8f, v71
	s_nop 0
	v_cndmask_b32_e32 v41, v176, v57, vcc
	v_cmp_lt_u32_e32 vcc, s29, v34
	v_add_u32_e32 v34, 0xffffffaf, v71
	s_nop 0
	v_cndmask_b32_e32 v57, v176, v42, vcc
	v_cmp_lt_u32_e32 vcc, s29, v34
	v_add_u32_e32 v34, 0xffffff90, v71
	s_nop 0
	v_cndmask_b32_e32 v42, v176, v58, vcc
	v_cmp_lt_u32_e32 vcc, s29, v34
	v_add_u32_e32 v34, 0xffffffb0, v71
	s_nop 0
	v_cndmask_b32_e32 v58, v176, v43, vcc
	v_cmp_lt_u32_e32 vcc, s29, v34
	v_add_u32_e32 v34, 0xffffff91, v71
	s_nop 0
	v_cndmask_b32_e32 v43, v176, v59, vcc
	v_cmp_lt_u32_e32 vcc, s29, v34
	v_add_u32_e32 v34, 0xffffffb1, v71
	s_nop 0
	v_cndmask_b32_e32 v59, v176, v44, vcc
	v_cmp_lt_u32_e32 vcc, s29, v34
	v_add_u32_e32 v34, 0xffffff92, v71
	s_nop 0
	v_cndmask_b32_e32 v44, v176, v60, vcc
	v_cmp_lt_u32_e32 vcc, s29, v34
	v_add_u32_e32 v34, 0xffffffb2, v71
	s_nop 0
	v_cndmask_b32_e32 v60, v176, v45, vcc
	v_cmp_lt_u32_e32 vcc, s29, v34
	v_add_u32_e32 v34, 0xffffff97, v71
	s_nop 0
	v_cndmask_b32_e32 v45, v176, v61, vcc
	v_cmp_lt_u32_e32 vcc, s29, v34
	v_add_u32_e32 v34, 0xffffffb7, v71
	s_nop 0
	v_cndmask_b32_e32 v61, v176, v46, vcc
	v_cmp_lt_u32_e32 vcc, s29, v34
	v_add_u32_e32 v34, 0xffffff98, v71
	s_nop 0
	v_cndmask_b32_e32 v46, v176, v62, vcc
	v_cmp_lt_u32_e32 vcc, s29, v34
	v_add_u32_e32 v34, 0xffffffb8, v71
	s_nop 0
	v_cndmask_b32_e32 v62, v176, v47, vcc
	v_cmp_lt_u32_e32 vcc, s29, v34
	v_add_u32_e32 v34, 0xffffff99, v71
	s_nop 0
	v_cndmask_b32_e32 v47, v176, v63, vcc
	v_cmp_lt_u32_e32 vcc, s29, v34
	v_add_u32_e32 v34, 0xffffffb9, v71
	s_nop 0
	v_cndmask_b32_e32 v37, v176, v48, vcc
	v_cmp_lt_u32_e32 vcc, s29, v34
	s_nop 1
	v_cndmask_b32_e32 v34, v176, v64, vcc
	v_cmp_lt_u32_e32 vcc, s29, v35
	v_add_u32_e32 v35, 0xffffffba, v71
	v_cndmask_b32_e32 v36, v176, v49, vcc
	v_cmp_lt_u32_e32 vcc, s29, v35
	v_cndmask_b32_e32 v35, v176, v65, vcc
.LBB0_796:
	v_exp_f32_e32 v64, v66
	v_exp_f32_e32 v66, v67
	v_exp_f32_e32 v65, v50
	v_exp_f32_e32 v67, v51
	v_exp_f32_e32 v50, v68
	v_exp_f32_e32 v68, v69
	v_exp_f32_e32 v51, v52
	v_mov_b32_e32 v48, v53
	v_exp_f32_e32 v53, v38
	v_exp_f32_e32 v69, v48
	v_exp_f32_e32 v71, v39
	v_exp_f32_e32 v52, v70
	v_mov_b32_e32 v48, v54
	v_exp_f32_e32 v54, v55
	v_exp_f32_e32 v72, v56
	v_exp_f32_e32 v55, v40
	v_exp_f32_e32 v73, v41
	v_exp_f32_e32 v56, v57
	v_exp_f32_e32 v74, v58
	v_exp_f32_e32 v57, v42
	v_exp_f32_e32 v75, v43
	v_exp_f32_e32 v58, v59
	v_exp_f32_e32 v76, v60
	v_exp_f32_e32 v59, v44
	v_exp_f32_e32 v77, v45
	v_exp_f32_e32 v60, v61
	s_bitcmp1_b32 s42, 0
	v_exp_f32_e32 v62, v62
	s_cselect_b32 s4, 0x3000, 0
	v_exp_f32_e32 v61, v46
	v_add_u32_e32 v82, s4, v183
	v_exp_f32_e32 v70, v48
	v_exp_f32_e32 v63, v47
	ds_read_b64_tr_b16 v[38:39], v82 offset:18432
	ds_read_b64_tr_b16 v[40:41], v82 offset:19968
	ds_read_b64_tr_b16 v[48:49], v82 offset:20032
	ds_read_b64_tr_b16 v[46:47], v82 offset:18496
	v_cvt_pk_bf16_f32 v42, v64, v66
	v_cvt_pk_bf16_f32 v43, v50, v68
	v_cvt_pk_bf16_f32 v44, v52, v70
	v_cvt_pk_bf16_f32 v45, v54, v72
	s_waitcnt lgkmcnt(2)
	v_mfma_f32_32x32x16_bf16 v[2:17], v[38:41], v[42:45], v[2:17]
	v_exp_f32_e32 v78, v37
	v_exp_f32_e32 v80, v36
	v_exp_f32_e32 v79, v34
	v_mov_b32_e32 v38, v35
	ds_read_b64_tr_b16 v[34:35], v82 offset:21504
	ds_read_b64_tr_b16 v[36:37], v82 offset:23040
	v_exp_f32_e32 v81, v38
	s_waitcnt lgkmcnt(2)
	v_mfma_f32_32x32x16_bf16 v[18:33], v[46:49], v[42:45], v[18:33]
	ds_read_b64_tr_b16 v[44:45], v82 offset:23104
	ds_read_b64_tr_b16 v[42:43], v82 offset:21568
	v_cvt_pk_bf16_f32 v38, v56, v74
	v_cvt_pk_bf16_f32 v39, v58, v76
	v_cvt_pk_bf16_f32 v40, v60, v62
	v_cvt_pk_bf16_f32 v41, v78, v80
	s_waitcnt lgkmcnt(2)
	s_nop 0
	v_mfma_f32_32x32x16_bf16 v[2:17], v[34:37], v[38:41], v[2:17]
	v_add_f32_e64 v34, v64, 0
	v_add_f32_e64 v35, v65, 0
	v_add_f32_e64 v36, v66, 0
	v_add_f32_e64 v37, v67, 0
	v_add_f32_e64 v34, v50, v34
	v_add_f32_e64 v35, v51, v35
	v_pk_add_f32 v[46:47], v[68:69], v[36:37]
	v_pk_add_f32 v[48:49], v[52:53], v[34:35]
	ds_read_b64_tr_b16 v[34:35], v82 offset:24576
	ds_read_b64_tr_b16 v[36:37], v82 offset:26112
	v_pk_add_f32 v[46:47], v[70:71], v[46:47]
	s_waitcnt lgkmcnt(2)
	v_mfma_f32_32x32x16_bf16 v[18:33], v[42:45], v[38:41], v[18:33]
	ds_read_b64_tr_b16 v[44:45], v82 offset:26176
	ds_read_b64_tr_b16 v[42:43], v82 offset:24640
	v_cvt_pk_bf16_f32 v38, v65, v67
	v_cvt_pk_bf16_f32 v39, v51, v69
	v_cvt_pk_bf16_f32 v40, v53, v71
	v_cvt_pk_bf16_f32 v41, v55, v73
	s_waitcnt lgkmcnt(2)
	s_nop 0
	v_mfma_f32_32x32x16_bf16 v[2:17], v[34:37], v[38:41], v[2:17]
	v_add_f32_e64 v34, v54, v48
	v_add_f32_e64 v35, v55, v49
	v_add_f32_e64 v36, v72, v46
	v_add_f32_e64 v37, v73, v47
	v_add_f32_e64 v34, v56, v34
	v_add_f32_e64 v35, v57, v35
	v_pk_add_f32 v[46:47], v[74:75], v[36:37]
	v_pk_add_f32 v[48:49], v[58:59], v[34:35]
	ds_read_b64_tr_b16 v[34:35], v82 offset:27648
	ds_read_b64_tr_b16 v[36:37], v82 offset:29184
	v_pk_add_f32 v[46:47], v[76:77], v[46:47]
	s_waitcnt lgkmcnt(2)
	v_mfma_f32_32x32x16_bf16 v[18:33], v[42:45], v[38:41], v[18:33]
	ds_read_b64_tr_b16 v[44:45], v82 offset:29248
	ds_read_b64_tr_b16 v[42:43], v82 offset:27712
	v_cvt_pk_bf16_f32 v38, v57, v75
	v_cvt_pk_bf16_f32 v39, v59, v77
	v_cvt_pk_bf16_f32 v40, v61, v63
	v_cvt_pk_bf16_f32 v41, v79, v81
	s_waitcnt lgkmcnt(0)
	s_barrier
	v_mfma_f32_32x32x16_bf16 v[2:17], v[34:37], v[38:41], v[2:17]
	v_add_f32_e64 v34, v60, v48
	v_add_f32_e64 v35, v61, v49
	v_add_f32_e64 v36, v62, v46
	v_add_f32_e64 v37, v63, v47
	v_add_f32_e64 v34, v78, v34
	v_add_f32_e64 v35, v79, v35
	v_pk_add_f32 v[36:37], v[80:81], v[36:37]
	s_nop 0
	v_pk_add_f32 v[34:35], v[34:35], v[36:37]
	v_mfma_f32_32x32x16_bf16 v[18:33], v[42:45], v[38:41], v[18:33]
	v_add_f32_e32 v34, v34, v35
	v_add_f32_e32 v0, v0, v34
